# RWKV scan chunk sync: arrival counters in LDS instead of s_barrier between chunks - scanner waves wait only for the 4 stager waves, stager waves wait for all 8 (first and last barrier of an item stay
# speedup vs baseline: 1.0123x; 1.0031x over previous
; template <int CPL>
; DI void scan_block2(CP p, int layer, int s, int d, int hd, int rowhalf, char* smem) {
;     ...
;     constexpr int LPRW = 64 / CPL;
;     constexpr int NV = CPL / 2;
;     const int cg = lane % LPRW;
;     const int row = (CPL == 8 ? rowhalf * 32 + wv * 8 : wv * 16) + lane / LPRW;
;     f2 S[NV];
; #pragma unroll
;     for (int i = 0; i < NV; ++i) S[i] = mk2(0.f, 0.f);
;     __builtin_amdgcn_s_setprio(3);
;     __syncthreads();
.LBB0_181:
	s_or_b64 exec, exec, s[2:3]
	v_ashrrev_i32_e32 v0, 6, v2
	s_and_b32 s16, s82, 1
	v_cmp_gt_i32_e32 vcc, 4, v0
	v_lshlrev_b32_e32 v52, 3, v0
	s_waitcnt lgkmcnt(0)
	s_barrier
	s_and_saveexec_b64 s[2:3], vcc
	s_xor_b64 s[2:3], exec, s[2:3]
	s_cbranch_execz .LBB0_187
	s_setprio 3
	v_and_b32_e32 v0, 63, v179
	v_lshrrev_b32_e32 v202, 6, v179
	v_and_b32_e32 v203, 7, v0
	v_lshrrev_b32_e32 v204, 3, v0
	v_lshl_add_u32 v204, v202, 3, v204
	s_lshl_b32 s8, s16, 5
	v_add_u32_e32 v204, s8, v204
	v_lshlrev_b32_e32 v202, 5, v203
	v_lshlrev_b32_e32 v204, 2, v204
	v_add_u32_e32 v205, 0x500, v204
	v_add_u32_e32 v204, 0x18800, v204
	v_lshlrev_b32_e32 v206, 2, v0
	v_add_u32_e32 v206, 0x24800, v206
	v_cmp_eq_u32_e32 vcc, 0, v203
	v_mov_b32_e32 v170, 0
	v_mov_b32_e32 v171, 0
	v_mov_b32_e32 v172, 0
	v_mov_b32_e32 v173, 0
	v_mov_b32_e32 v174, 0
	v_mov_b32_e32 v175, 0
	v_mov_b32_e32 v176, 0
	v_mov_b32_e32 v177, 0
	s_mov_b32 s10, 0
	v_lshrrev_b32_e32 v2, 6, v179
	v_lshlrev_b32_e32 v2, 2, v2
	v_add_u32_e32 v2, 0x26800, v2
	v_mov_b32_e32 v3, 0
	ds_write_b32 v2, v3
	s_waitcnt lgkmcnt(0)
	s_barrier

; template <int CPL>
; DI void scan_block2(CP p, int layer, int s, int d, int hd, int rowhalf, char* smem) {
;     ...
;       __syncthreads();
.Lsc8_next:
	s_waitcnt lgkmcnt(0)
	s_cmp_eq_u32 s10, 0x100
	s_cbranch_scc1 .Lsc8_realbar
	s_add_i32 s8, s10, 1
	v_lshrrev_b32_e32 v2, 6, v179
	v_lshlrev_b32_e32 v2, 2, v2
	v_add_u32_e32 v2, 0x26800, v2
	v_mov_b32_e32 v3, s8
	v_mov_b32_e32 v4, 0x26810
	v_mov_b32_e32 v5, 0x26800
	ds_write_b32 v2, v3
	s_movk_i32 s15, 1000
.Lsc8_poll:
	ds_read_b128 v[6:9], v4
	s_waitcnt lgkmcnt(0)
	v_min_u32_e32 v6, v6, v7
	v_min_u32_e32 v8, v8, v9
	s_nop 0
	v_min_u32_e32 v6, v6, v8
	s_nop 1
	v_readfirstlane_b32 s17, v6
	s_nop 0
	s_cmp_ge_u32 s17, s8
	s_cbranch_scc1 .Lsc8_passed
	s_sleep 1
	s_sub_i32 s15, s15, 1
	s_cmp_gt_i32 s15, 0
	s_cbranch_scc1 .Lsc8_poll

; template <int CPL>
; DI void scan_block2(CP p, int layer, int s, int d, int hd, int rowhalf, char* smem) {
;     ...
;     for (int c = 0; c < nch; ++c) {
;       const int nst = min(32, L - c * 32);
;     ...
;       __syncthreads();
.Lsc8_realbar:
	s_barrier
.Lsc8_after:
	s_add_i32 s10, s10, 1
	s_cmp_eq_u32 s10, 0x101
	s_cbranch_scc0 .Lsc8_chunk
	s_branch .Lsc8_done

; template <int CPL>
; DI void scan_block2(CP p, int layer, int s, int d, int hd, int rowhalf, char* smem) {
;     ...
;     auto load_raw = [&](int c) {
; #pragma unroll
;       for (int u = 0; u < 2; ++u) {
;         const int sj = 8 * sw + 4 * u + (lane >> 4);
;         const int sidc = min(c * 32 + sj, L - 1);
;         const int tok = d == 0 ? sidc : L - 1 - sidc;
;         const u16* base = p.regB + (size_t)(r0 + tok) * 1952 + 4 * q;
;         raw[u][0] = *(const uint2*)(base + aoff0); raw[u][1] = *(const uint2*)(base + aoff1); raw[u][2] = *(const uint2*)(base + aoff2);
;         raw[u][3] = *(const uint2*)(base + aoff3); raw[u][4] = *(const uint2*)(base + aoff4);
;       }
;     };
;     ...
;     load_raw(0);
;     stage(0);
;     if (nch > 1) load_raw(1);
;     __syncthreads();
.LBB0_194:
	s_or_b64 exec, exec, s[2:3]
	v_min_u32_e32 v0, 0x200f, v47
	v_sub_u32_e32 v3, 0x200f, v0
	v_cndmask_b32_e32 v0, v3, v0, vcc
	v_add_u32_e32 v0, s15, v0
	v_mov_b64_e32 v[4:5], s[66:67]
	v_mad_i64_i32 v[6:7], s[2:3], v0, s88, v[4:5]
	v_lshlrev_b32_e32 v0, 1, v76
	v_lshl_add_u64 v[6:7], v[6:7], 0, v[0:1]
	s_mov_b32 s73, s77
	v_lshl_add_u64 v[8:9], v[6:7], 0, s[76:77]
	v_lshl_add_u64 v[6:7], v[6:7], 0, s[72:73]
	global_load_dwordx2 v[10:11], v[8:9], off
	global_load_dwordx2 v[12:13], v[8:9], off offset:1024
	s_nop 0
	global_load_dwordx2 v[8:9], v[8:9], off offset:2048
	s_nop 0
	global_load_dwordx2 v[14:15], v[6:7], off offset:3072
	s_nop 0
	global_load_dwordx2 v[6:7], v[6:7], off offset:3328
	v_or_b32_e32 v3, 4, v47
	v_min_u32_e32 v3, 0x200f, v3
	v_sub_u32_e32 v16, 0x200f, v3
	v_cndmask_b32_e32 v3, v16, v3, vcc
	v_add_u32_e32 v3, s15, v3
	v_mad_i64_i32 v[4:5], s[2:3], v3, s88, v[4:5]
	v_lshl_add_u64 v[4:5], v[4:5], 0, v[0:1]
	v_lshl_add_u64 v[16:17], v[4:5], 0, s[76:77]
	v_lshl_add_u64 v[4:5], v[4:5], 0, s[72:73]
	global_load_dwordx2 v[32:33], v[16:17], off
	global_load_dwordx2 v[26:27], v[16:17], off offset:1024
	global_load_dwordx2 v[30:31], v[16:17], off offset:2048
	s_nop 0
	global_load_dwordx2 v[16:17], v[4:5], off offset:3072
	global_load_dwordx2 v[42:43], v[4:5], off offset:3328
	s_mov_b64 s[98:99], exec
	s_mov_b64 exec, -1
	v_and_b32_e32 v105, 63, v179
	v_lshlrev_b32_e32 v105, 2, v105
	v_lshrrev_b32_e32 v106, 6, v179
	v_add_u32_e32 v106, -4, v106
	v_mul_u32_u24_e32 v106, 0x3100, v106
	v_mov_b32_e32 v107, 0x0
	v_add3_u32 v105, v105, v106, v107
	s_waitcnt lgkmcnt(0)
	ds_read_b32 v109, v105 offset:256
	ds_read_b32 v110, v105 offset:512
	ds_read_b32 v111, v105 offset:768
	ds_read_b32 v112, v105 offset:1024
	s_waitcnt lgkmcnt(0)
	v_mov_b32_e32 v113, v110
	v_rcp_f32_e32 v114, v113
	v_mul_f32_e32 v109, v109, v113
	v_mul_f32_e32 v111, v111, v114
	v_mul_f32_e32 v112, v112, v114
	ds_write_b32 v105, v109 offset:256
	ds_write_b32 v105, v111 offset:768
	ds_write_b32 v105, v112 offset:1024
	ds_read_b32 v108, v105 offset:1568
	ds_read_b32 v109, v105 offset:1824
	ds_read_b32 v110, v105 offset:2080
	ds_read_b32 v111, v105 offset:2336
	ds_read_b32 v112, v105 offset:2592
	s_waitcnt lgkmcnt(0)
	v_mul_f32_e32 v108, v108, v113
	v_mul_f32_e32 v113, v113, v110
	v_rcp_f32_e32 v114, v113
	v_mul_f32_e32 v109, v109, v113
	v_mul_f32_e32 v111, v111, v114
	v_mul_f32_e32 v112, v112, v114
	ds_write_b32 v105, v108 offset:1568
	ds_write_b32 v105, v109 offset:1824
	ds_write_b32 v105, v113 offset:2080
	ds_write_b32 v105, v111 offset:2336
	ds_write_b32 v105, v112 offset:2592
	ds_read_b32 v108, v105 offset:3136
	ds_read_b32 v109, v105 offset:3392
	ds_read_b32 v110, v105 offset:3648
	ds_read_b32 v111, v105 offset:3904
	ds_read_b32 v112, v105 offset:4160
	s_waitcnt lgkmcnt(0)
	v_mul_f32_e32 v108, v108, v113
	v_mul_f32_e32 v113, v113, v110
	v_rcp_f32_e32 v114, v113
	v_mul_f32_e32 v109, v109, v113
	v_mul_f32_e32 v111, v111, v114
	v_mul_f32_e32 v112, v112, v114
	ds_write_b32 v105, v108 offset:3136
	ds_write_b32 v105, v109 offset:3392
	ds_write_b32 v105, v113 offset:3648
	ds_write_b32 v105, v111 offset:3904
	ds_write_b32 v105, v112 offset:4160
	ds_read_b32 v108, v105 offset:4704
	ds_read_b32 v109, v105 offset:4960
	ds_read_b32 v110, v105 offset:5216
	ds_read_b32 v111, v105 offset:5472
	ds_read_b32 v112, v105 offset:5728
	s_waitcnt lgkmcnt(0)
	v_mul_f32_e32 v108, v108, v113
	v_mul_f32_e32 v113, v113, v110
	v_rcp_f32_e32 v114, v113
	v_mul_f32_e32 v109, v109, v113
	v_mul_f32_e32 v111, v111, v114
	v_mul_f32_e32 v112, v112, v114
	ds_write_b32 v105, v108 offset:4704
	ds_write_b32 v105, v109 offset:4960
	ds_write_b32 v105, v113 offset:5216
	ds_write_b32 v105, v111 offset:5472
	ds_write_b32 v105, v112 offset:5728
	ds_read_b32 v108, v105 offset:6272
	ds_read_b32 v109, v105 offset:6528
	ds_read_b32 v110, v105 offset:6784
	ds_read_b32 v111, v105 offset:7040
	ds_read_b32 v112, v105 offset:7296
	s_waitcnt lgkmcnt(0)
	v_mul_f32_e32 v108, v108, v113
	v_mul_f32_e32 v113, v113, v110
	v_rcp_f32_e32 v114, v113
	v_mul_f32_e32 v109, v109, v113
	v_mul_f32_e32 v111, v111, v114
	v_mul_f32_e32 v112, v112, v114
	ds_write_b32 v105, v108 offset:6272
	ds_write_b32 v105, v109 offset:6528
	ds_write_b32 v105, v113 offset:6784
	ds_write_b32 v105, v111 offset:7040
	ds_write_b32 v105, v112 offset:7296
	ds_read_b32 v108, v105 offset:7840
	ds_read_b32 v109, v105 offset:8096
	ds_read_b32 v110, v105 offset:8352
	ds_read_b32 v111, v105 offset:8608
	ds_read_b32 v112, v105 offset:8864
	s_waitcnt lgkmcnt(0)
	v_mul_f32_e32 v108, v108, v113
	v_mul_f32_e32 v113, v113, v110
	v_rcp_f32_e32 v114, v113
	v_mul_f32_e32 v109, v109, v113
	v_mul_f32_e32 v111, v111, v114
	v_mul_f32_e32 v112, v112, v114
	ds_write_b32 v105, v108 offset:7840
	ds_write_b32 v105, v109 offset:8096
	ds_write_b32 v105, v113 offset:8352
	ds_write_b32 v105, v111 offset:8608
	ds_write_b32 v105, v112 offset:8864
	ds_read_b32 v108, v105 offset:9408
	ds_read_b32 v109, v105 offset:9664
	ds_read_b32 v110, v105 offset:9920
	ds_read_b32 v111, v105 offset:10176
	ds_read_b32 v112, v105 offset:10432
	s_waitcnt lgkmcnt(0)
	v_mul_f32_e32 v108, v108, v113
	v_mul_f32_e32 v113, v113, v110
	v_rcp_f32_e32 v114, v113
	v_mul_f32_e32 v109, v109, v113
	v_mul_f32_e32 v111, v111, v114
	v_mul_f32_e32 v112, v112, v114
	ds_write_b32 v105, v108 offset:9408
	ds_write_b32 v105, v109 offset:9664
	ds_write_b32 v105, v113 offset:9920
	ds_write_b32 v105, v111 offset:10176
	ds_write_b32 v105, v112 offset:10432
	ds_read_b32 v108, v105 offset:10976
	ds_read_b32 v110, v105 offset:11488
	ds_read_b32 v111, v105 offset:11744
	ds_read_b32 v112, v105 offset:12000
	s_waitcnt lgkmcnt(0)
	v_mul_f32_e32 v108, v108, v113
	v_mul_f32_e32 v113, v113, v110
	v_rcp_f32_e32 v114, v113
	s_nop 0
	v_mul_f32_e32 v111, v111, v114
	v_mul_f32_e32 v112, v112, v114
	ds_write_b32 v105, v108 offset:10976
	ds_write_b32 v105, v113 offset:11488
	ds_write_b32 v105, v111 offset:11744
	ds_write_b32 v105, v112 offset:12000
	s_mov_b64 exec, s[98:99]
	v_lshrrev_b32_e32 v121, 6, v179
	v_lshlrev_b32_e32 v121, 2, v121
	v_add_u32_e32 v121, 0x26800, v121
	v_mov_b32_e32 v124, 0
	ds_write_b32 v121, v124
	s_waitcnt lgkmcnt(0)
	s_barrier
; #define MFMA(a, b, c) __builtin_amdgcn_mfma_f32_32x32x16_bf16((a), (b), (c), 0, 0, 0)
; DI float bflo(unsigned u) { return __uint_as_float(u << 16); }
; DI float bfhi(unsigned u) { return __uint_as_float(u & 0xffff0000u); }
; template <int CPL>
; DI void scan_block2(CP p, int layer, int s, int d, int hd, int rowhalf, char* smem) {
;     ...
;     auto stage = [&](int c) {
;       float r4[2][4], k4[2][4], kk4[2][4], v4[2][4];
; #pragma unroll
;       for (int u = 0; u < 2; ++u) {
;         const int sj = 8 * sw + 4 * u + (lane >> 4);
;         r4[u][0] = bflo(raw[u][0].x); r4[u][1] = bfhi(raw[u][0].x); r4[u][2] = bflo(raw[u][0].y); r4[u][3] = bfhi(raw[u][0].y);
;         k4[u][0] = bflo(raw[u][1].x); k4[u][1] = bfhi(raw[u][1].x); k4[u][2] = bflo(raw[u][1].y); k4[u][3] = bfhi(raw[u][1].y);
;         v4[u][0] = bflo(raw[u][2].x); v4[u][1] = bfhi(raw[u][2].x); v4[u][2] = bflo(raw[u][2].y); v4[u][3] = bfhi(raw[u][2].y);
;         *(uint2*)(XL + sj * 72 + 4 * q) = raw[u][3];
;         *(uint2*)(XL + 32 * 72 + sj * 72 + 4 * q) = raw[u][4];
;         const float4 kkw = *(const float4*)(CS + 4 * q);
;         float x0 = k4[u][0] * kkw.x, x1 = k4[u][1] * kkw.y, x2 = k4[u][2] * kkw.z, x3 = k4[u][3] * kkw.w;
;         float ss = sum16(x0 * x0 + x1 * x1 + x2 * x2 + x3 * x3);
;         float inv = __builtin_amdgcn_rsqf(fmaxf(ss, 1e-24f));
;         kk4[u][0] = x0 * inv; kk4[u][1] = x1 * inv; kk4[u][2] = x2 * inv; kk4[u][3] = x3 * inv;
;       }
;       LDS_FENCE();
;       float* OPn = OP + (c & 1) * 32 * 392;
; #pragma unroll
;       for (int mat = 0; mat < 2; ++mat)
; #pragma unroll
;         for (int nt2 = 0; nt2 < 2; ++nt2) {
;           f32x16 acc;
; #pragma unroll
;           for (int r = 0; r < 16; ++r) acc[r] = 0.f;
;           const u16* xb = XL + mat * 32 * 72 + (8 * sw + (l32 & 7)) * 72 + hh * 8;
; #pragma unroll
;           for (int ks = 0; ks < 4; ++ks) acc = MFMA(*(const bf16x8*)(xb + ks * 16), *(const bf16x8*)(WL + (mat * 64 + nt2 * 32 + l32) * 72 + ks * 16 + hh * 8), acc);
; #pragma unroll
;           for (int r = 0; r < 4; ++r) {
;             float x = acc[r] + bias[mat][nt2];
;             float sg = sigmoidf_(x);
;             float val = mat ? sg : __expf(-0.6065306597126334f * sg);
;             OPn[(8 * sw + 4 * hh + r) * 392 + (mat ? 0 : 128) + nt2 * 32 + l32] = val;
;           }
;         }
;       LDS_FENCE();
	v_mov_b32_e32 v120, 0
	v_lshlrev_b32_e32 v2, 2, v2
	v_mov_b32_e32 v3, v1
	v_lshl_add_u64 v[36:37], s[64:65], 0, v[2:3]
	v_mul_u32_u24_e32 v78, 0x90, v46
	v_add_u32_e32 v79, 0x240, v67
	v_add_u32_e32 v80, 0x240, v68
	v_add_u32_e32 v78, v51, v78
	s_cmp_eq_u32 s16, 0
	s_movk_i32 s2, 0x1ff0
	s_cselect_b64 s[74:75], -1, 0
	v_cmp_gt_u32_e64 s[44:45], s2, v50
	v_cmp_eq_u32_e64 s[40:41], 0, v75
	v_mov_b32_e32 v83, v1
	s_and_b64 s[2:3], s[74:75], s[44:45]
	v_cmp_ne_u32_e64 s[42:43], 0, v75
	s_and_b64 s[10:11], s[40:41], s[2:3]
	s_waitcnt vmcnt(6)
	ds_write_b64 v67, v[14:15]
	s_waitcnt vmcnt(5)
	ds_write_b64 v68, v[6:7]
	ds_read_b128 v[2:5], v69
	v_lshlrev_b32_e32 v48, 16, v12
	v_and_b32_e32 v49, 0xffff0000, v12
	v_lshlrev_b32_e32 v46, 16, v13
	v_and_b32_e32 v47, 0xffff0000, v13
	s_waitcnt lgkmcnt(0)
	v_pk_mul_f32 v[2:3], v[2:3], v[48:49]
	v_pk_mul_f32 v[4:5], v[4:5], v[46:47]
	v_pk_mul_f32 v[6:7], v[2:3], v[2:3]
	v_lshlrev_b32_e32 v18, 16, v8
	v_and_b32_e32 v19, 0xffff0000, v8
	v_lshlrev_b32_e32 v20, 16, v9
	v_and_b32_e32 v21, 0xffff0000, v9
	v_pk_mul_f32 v[8:9], v[4:5], v[4:5]
	v_add_f32_e32 v6, v6, v7
	v_add_f32_e32 v6, v6, v8
	v_add_f32_e32 v6, v6, v9
	s_waitcnt vmcnt(1)
	ds_write_b64 v79, v[16:17]
	s_waitcnt vmcnt(0)
	ds_write_b64 v80, v[42:43]
	v_add_f32_dpp v6, v6, v6 row_ror:8 row_mask:0xf bank_mask:0xf bound_ctrl:1
	v_lshlrev_b32_e32 v40, 16, v26
	v_and_b32_e32 v41, 0xffff0000, v26
	v_add_f32_dpp v6, v6, v6 row_ror:4 row_mask:0xf bank_mask:0xf bound_ctrl:1
	v_lshlrev_b32_e32 v38, 16, v27
	v_and_b32_e32 v39, 0xffff0000, v27
	v_add_f32_dpp v6, v6, v6 row_ror:2 row_mask:0xf bank_mask:0xf bound_ctrl:1
	v_lshlrev_b32_e32 v22, 16, v10
	v_and_b32_e32 v23, 0xffff0000, v10
	v_add_f32_dpp v6, v6, v6 row_ror:1 row_mask:0xf bank_mask:0xf bound_ctrl:1
	v_max_f32_e32 v6, 0x179abe15, v6
	v_rsq_f32_e32 v6, v6
	v_lshlrev_b32_e32 v24, 16, v11
	v_and_b32_e32 v25, 0xffff0000, v11
	v_pk_mul_f32 v[26:27], v[2:3], v[6:7] op_sel_hi:[1,0]
	v_pk_mul_f32 v[28:29], v[4:5], v[6:7] op_sel_hi:[1,0]
	ds_read_b128 v[2:5], v69
	s_waitcnt lgkmcnt(0)
	s_waitcnt lgkmcnt(0)
	v_pk_mul_f32 v[42:43], v[2:3], v[40:41]
	v_pk_mul_f32 v[44:45], v[4:5], v[38:39]
	v_pk_mul_f32 v[2:3], v[42:43], v[42:43]
	v_pk_mul_f32 v[4:5], v[44:45], v[44:45]
	v_add_f32_e32 v2, v2, v3
	v_add_f32_e32 v2, v2, v4
	v_add_f32_e32 v2, v2, v5
	s_nop 1
	v_add_f32_dpp v2, v2, v2 row_ror:8 row_mask:0xf bank_mask:0xf bound_ctrl:1
	s_nop 1
	v_add_f32_dpp v2, v2, v2 row_ror:4 row_mask:0xf bank_mask:0xf bound_ctrl:1
	s_nop 1
	v_add_f32_dpp v82, v2, v2 row_ror:2 row_mask:0xf bank_mask:0xf bound_ctrl:1
	ds_read_b128 v[2:5], v62
	ds_read_b128 v[84:87], v62 offset:32
	ds_read_b128 v[6:9], v78
	ds_read_b128 v[88:91], v78 offset:32
	s_waitcnt lgkmcnt(1)
	v_mfma_f32_32x32x16_bf16 v[2:17], v[2:5], v[6:9], 0
	v_mov_b32_dpp v83, v82 row_ror:1 row_mask:0xf bank_mask:0xf
	s_waitcnt lgkmcnt(0)
	v_mfma_f32_32x32x16_bf16 v[2:17], v[84:87], v[88:91], v[2:17]
	ds_read_b128 v[84:87], v62 offset:64
	ds_read_b128 v[88:91], v78 offset:64
	s_waitcnt lgkmcnt(0)
	v_mfma_f32_32x32x16_bf16 v[2:17], v[84:87], v[88:91], v[2:17]
	ds_read_b128 v[84:87], v62 offset:96
	ds_read_b128 v[88:91], v78 offset:96
	s_waitcnt lgkmcnt(0)
	v_mfma_f32_32x32x16_bf16 v[2:17], v[84:87], v[88:91], v[2:17]
	s_nop 11
	v_add_f32_e32 v2, v64, v2
	v_mul_f32_e32 v2, 0xbfb8aa3b, v2
	v_exp_f32_e32 v2, v2
	s_nop 0
	v_add_f32_e32 v2, 1.0, v2
	v_rcp_f32_e32 v2, v2
	s_nop 0
	v_mul_f32_e32 v2, 0xbf1b4598, v2
	v_mul_f32_e32 v2, 0x3fb8aa3b, v2
	v_exp_f32_e32 v2, v2
	ds_write_b32 v59, v2 offset:50688
	v_add_f32_e32 v2, v64, v3
	v_mul_f32_e32 v2, 0xbfb8aa3b, v2
	v_exp_f32_e32 v2, v2
	s_nop 0
	v_add_f32_e32 v2, 1.0, v2
	v_rcp_f32_e32 v2, v2
	s_nop 0
	v_mul_f32_e32 v2, 0xbf1b4598, v2
	v_mul_f32_e32 v2, 0x3fb8aa3b, v2
	v_exp_f32_e32 v2, v2
	ds_write_b32 v66, v2 offset:51744
	v_add_f32_e32 v2, v64, v4
	v_mul_f32_e32 v2, 0xbfb8aa3b, v2
	v_exp_f32_e32 v2, v2
	s_nop 0
	v_add_f32_e32 v2, 1.0, v2
	v_rcp_f32_e32 v2, v2
	s_nop 0
	v_mul_f32_e32 v2, 0xbf1b4598, v2
	v_mul_f32_e32 v2, 0x3fb8aa3b, v2
	v_exp_f32_e32 v2, v2
	ds_write_b32 v66, v2 offset:53312
	v_add_f32_e32 v2, v64, v5
	v_mul_f32_e32 v2, 0xbfb8aa3b, v2
	v_exp_f32_e32 v2, v2
	s_nop 0
	v_add_f32_e32 v2, 1.0, v2
	v_rcp_f32_e32 v2, v2
	s_nop 0
	v_mul_f32_e32 v2, 0xbf1b4598, v2
	v_mul_f32_e32 v2, 0x3fb8aa3b, v2
	v_exp_f32_e32 v2, v2
	ds_write_b32 v66, v2 offset:54880
	ds_read_b128 v[2:5], v62
	ds_read_b128 v[84:87], v62 offset:32
	ds_read_b128 v[6:9], v78 offset:4608
	ds_read_b128 v[88:91], v78 offset:4640
	s_waitcnt lgkmcnt(1)
	v_mfma_f32_32x32x16_bf16 v[2:17], v[2:5], v[6:9], 0
	s_waitcnt lgkmcnt(0)
	v_mfma_f32_32x32x16_bf16 v[2:17], v[84:87], v[88:91], v[2:17]
	ds_read_b128 v[84:87], v62 offset:64
	ds_read_b128 v[88:91], v78 offset:4672
	s_waitcnt lgkmcnt(0)
	v_mfma_f32_32x32x16_bf16 v[2:17], v[84:87], v[88:91], v[2:17]
	ds_read_b128 v[84:87], v62 offset:96
	ds_read_b128 v[88:91], v78 offset:4704
	s_waitcnt lgkmcnt(0)
; template <int CPL>
; DI void scan_block2(CP p, int layer, int s, int d, int hd, int rowhalf, char* smem) {
;     ...
; #pragma unroll
;       for (int mat = 0; mat < 2; ++mat)
; #pragma unroll
;         for (int nt2 = 0; nt2 < 2; ++nt2) {
;           f32x16 acc;
; #pragma unroll
;           for (int r = 0; r < 16; ++r) acc[r] = 0.f;
;           const u16* xb = XL + mat * 32 * 72 + (8 * sw + (l32 & 7)) * 72 + hh * 8;
; #pragma unroll
;           for (int ks = 0; ks < 4; ++ks) acc = MFMA(*(const bf16x8*)(xb + ks * 16), *(const bf16x8*)(WL + (mat * 64 + nt2 * 32 + l32) * 72 + ks * 16 + hh * 8), acc);
; #pragma unroll
;           for (int r = 0; r < 4; ++r) {
;             float x = acc[r] + bias[mat][nt2];
;             float sg = sigmoidf_(x);
;             float val = mat ? sg : __expf(-0.6065306597126334f * sg);
;             OPn[(8 * sw + 4 * hh + r) * 392 + (mat ? 0 : 128) + nt2 * 32 + l32] = val;
;           }
;         }
;       LDS_FENCE();
; #pragma unroll
;       for (int u = 0; u < 2; ++u) {
;         const int sj = 8 * sw + 4 * u + (lane >> 4);
;         const float4 w4 = *(const float4*)(OPn + sj * 392 + 128 + 4 * q);
;         const float4 a4 = *(const float4*)(OPn + sj * 392 + 4 * q);
;         const float4 ka = *(const float4*)(CS + 64 + 4 * q);
;         const float4 brk = *(const float4*)(CS + 128 + 4 * q);
;         const float wv4[4] = {w4.x, w4.y, w4.z, w4.w}, av4[4] = {a4.x, a4.y, a4.z, a4.w};
;         const float kav[4] = {ka.x, ka.y, ka.z, ka.w}, bkv[4] = {brk.x, brk.y, brk.z, brk.w};
;         float bb[4], kd[4];
;         float bs = 0.f;
; #pragma unroll
;         for (int e = 0; e < 4; ++e) {
;           bb[e] = -kk4[u][e] * av4[e];
;           kd[e] = k4[u][e] * (1.f + (av4[e] - 1.f) * kav[e]);
;           bs += r4[u][e] * kd[e] * bkv[e];
;         }
;         bs = sum16(bs);
;         float* o = OPn + sj * 392 + 4 * q;
;         *(float4*)(o) = make_float4(kk4[u][0], kk4[u][1], kk4[u][2], kk4[u][3]);
;         *(float4*)(o + 64) = make_float4(r4[u][0], r4[u][1], r4[u][2], r4[u][3]);
;         *(float4*)(o + 128) = w4;
;         *(float4*)(o + 192) = make_float4(bb[0], bb[1], bb[2], bb[3]);
;         *(float4*)(o + 256) = make_float4(kd[0], kd[1], kd[2], kd[3]);
;         *(float4*)(o + 320) = make_float4(v4[u][0], v4[u][1], v4[u][2], v4[u][3]);
;         if (q == 0) {
;           const int sidx = c * 32 + sj;
	v_mfma_f32_32x32x16_bf16 v[2:17], v[84:87], v[88:91], v[2:17]
	s_nop 11
	v_add_f32_e32 v2, v63, v2
	v_mul_f32_e32 v2, 0xbfb8aa3b, v2
	v_exp_f32_e32 v2, v2
	s_nop 0
	v_add_f32_e32 v2, 1.0, v2
	v_rcp_f32_e32 v2, v2
	s_nop 0
	v_mul_f32_e32 v2, 0xbf1b4598, v2
	v_mul_f32_e32 v2, 0x3fb8aa3b, v2
	v_exp_f32_e32 v2, v2
	ds_write_b32 v59, v2 offset:50816
	v_add_f32_e32 v2, v63, v3
	v_mul_f32_e32 v2, 0xbfb8aa3b, v2
	v_exp_f32_e32 v2, v2
	s_nop 0
	v_add_f32_e32 v2, 1.0, v2
	v_rcp_f32_e32 v2, v2
	s_nop 0
	v_mul_f32_e32 v2, 0xbf1b4598, v2
	v_mul_f32_e32 v2, 0x3fb8aa3b, v2
	v_exp_f32_e32 v2, v2
	ds_write_b32 v65, v2 offset:51744
	v_add_f32_e32 v2, v63, v4
	v_mul_f32_e32 v2, 0xbfb8aa3b, v2
	v_exp_f32_e32 v2, v2
	s_nop 0
	v_add_f32_e32 v2, 1.0, v2
	v_rcp_f32_e32 v2, v2
	s_nop 0
	v_mul_f32_e32 v2, 0xbf1b4598, v2
	v_mul_f32_e32 v2, 0x3fb8aa3b, v2
	v_exp_f32_e32 v2, v2
	ds_write_b32 v65, v2 offset:53312
	v_add_f32_e32 v2, v63, v5
	v_mul_f32_e32 v2, 0xbfb8aa3b, v2
	v_exp_f32_e32 v2, v2
	s_nop 0
	v_add_f32_e32 v2, 1.0, v2
	v_rcp_f32_e32 v2, v2
	s_nop 0
	v_mul_f32_e32 v2, 0xbf1b4598, v2
	v_mul_f32_e32 v2, 0x3fb8aa3b, v2
	v_exp_f32_e32 v2, v2
	ds_write_b32 v65, v2 offset:54880
	ds_read_b128 v[2:5], v62 offset:4608
	ds_read_b128 v[84:87], v62 offset:4640
	ds_read_b128 v[6:9], v78 offset:9216
	ds_read_b128 v[88:91], v78 offset:9248
	s_waitcnt lgkmcnt(1)
	v_mfma_f32_32x32x16_bf16 v[2:17], v[2:5], v[6:9], 0
	s_waitcnt lgkmcnt(0)
	v_mfma_f32_32x32x16_bf16 v[2:17], v[84:87], v[88:91], v[2:17]
	ds_read_b128 v[84:87], v62 offset:4672
	ds_read_b128 v[88:91], v78 offset:9280
	s_waitcnt lgkmcnt(0)
	v_mfma_f32_32x32x16_bf16 v[2:17], v[84:87], v[88:91], v[2:17]
	ds_read_b128 v[84:87], v62 offset:4704
	ds_read_b128 v[88:91], v78 offset:9312
	s_waitcnt lgkmcnt(0)
	v_mfma_f32_32x32x16_bf16 v[2:17], v[84:87], v[88:91], v[2:17]
	s_nop 11
	v_add_f32_e32 v2, v56, v2
	v_mul_f32_e32 v2, 0xbfb8aa3b, v2
	v_exp_f32_e32 v2, v2
	s_nop 0
	v_add_f32_e32 v2, 1.0, v2
	v_rcp_f32_e32 v2, v2
	ds_write_b32 v59, v2 offset:50176
	v_add_f32_e32 v2, v56, v3
	v_mul_f32_e32 v2, 0xbfb8aa3b, v2
	v_exp_f32_e32 v2, v2
	s_nop 0
	v_add_f32_e32 v2, 1.0, v2
	v_rcp_f32_e32 v2, v2
	ds_write_b32 v59, v2 offset:51744
	v_add_f32_e32 v2, v56, v4
	v_mul_f32_e32 v2, 0xbfb8aa3b, v2
	v_exp_f32_e32 v2, v2
	s_nop 0
	v_add_f32_e32 v2, 1.0, v2
	v_rcp_f32_e32 v2, v2
	ds_write_b32 v59, v2 offset:53312
	v_add_f32_e32 v2, v56, v5
	v_mul_f32_e32 v2, 0xbfb8aa3b, v2
	v_exp_f32_e32 v2, v2
	s_nop 0
	v_add_f32_e32 v2, 1.0, v2
	v_rcp_f32_e32 v2, v2
	ds_write_b32 v59, v2 offset:54880
	ds_read_b128 v[2:5], v62 offset:4608
	ds_read_b128 v[84:87], v62 offset:4640
	ds_read_b128 v[6:9], v78 offset:13824
	ds_read_b128 v[88:91], v78 offset:13856
	s_waitcnt lgkmcnt(1)
	v_mfma_f32_32x32x16_bf16 v[2:17], v[2:5], v[6:9], 0
	s_waitcnt lgkmcnt(0)
	v_mfma_f32_32x32x16_bf16 v[2:17], v[84:87], v[88:91], v[2:17]
	ds_read_b128 v[84:87], v62 offset:4672
	ds_read_b128 v[88:91], v78 offset:13888
	s_waitcnt lgkmcnt(0)
	v_mfma_f32_32x32x16_bf16 v[2:17], v[84:87], v[88:91], v[2:17]
	ds_read_b128 v[84:87], v62 offset:4704
	ds_read_b128 v[88:91], v78 offset:13920
	s_waitcnt lgkmcnt(0)
	v_mfma_f32_32x32x16_bf16 v[2:17], v[84:87], v[88:91], v[2:17]
	s_nop 11
	v_add_f32_e32 v2, v55, v2
	v_mul_f32_e32 v2, 0xbfb8aa3b, v2
	v_exp_f32_e32 v2, v2
	s_nop 0
	v_add_f32_e32 v2, 1.0, v2
	v_rcp_f32_e32 v2, v2
	ds_write_b32 v59, v2 offset:50304
	v_add_f32_e32 v2, v55, v3
	v_mul_f32_e32 v2, 0xbfb8aa3b, v2
	v_exp_f32_e32 v2, v2
	s_nop 0
	v_add_f32_e32 v2, 1.0, v2
	v_rcp_f32_e32 v2, v2
	ds_write_b32 v60, v2 offset:51744
	v_add_f32_e32 v2, v55, v4
	v_mul_f32_e32 v2, 0xbfb8aa3b, v2
	v_exp_f32_e32 v2, v2
	s_nop 0
	v_add_f32_e32 v2, 1.0, v2
	v_rcp_f32_e32 v2, v2
	ds_write_b32 v60, v2 offset:53312
	v_add_f32_e32 v2, v55, v5
	v_mul_f32_e32 v2, 0xbfb8aa3b, v2
	v_exp_f32_e32 v2, v2
	s_nop 0
	v_add_f32_e32 v2, 1.0, v2
	v_rcp_f32_e32 v2, v2
	ds_write_b32 v60, v2 offset:54880
	s_waitcnt lgkmcnt(0)
	ds_read_b128 v[2:5], v61
	ds_read_b128 v[10:13], v57 offset:50176
	ds_write_b128 v57, v[22:25] offset:50432
	s_waitcnt lgkmcnt(1)
	v_pk_mul_f32 v[6:7], v[10:11], v[26:27] neg_lo:[0,1] neg_hi:[0,1]
	v_pk_mul_f32 v[8:9], v[12:13], v[28:29] neg_lo:[0,1] neg_hi:[0,1]
	ds_write_b128 v57, v[26:29] offset:50176
	ds_write_b128 v57, v[6:9] offset:50944
	ds_read_b128 v[6:9], v58
	v_pk_add_f32 v[10:11], v[10:11], -1.0 op_sel_hi:[1,0]
	v_pk_add_f32 v[12:13], v[12:13], -1.0 op_sel_hi:[1,0]
	s_waitcnt lgkmcnt(0)
	v_pk_fma_f32 v[10:11], v[10:11], v[6:7], 1.0 op_sel_hi:[1,1,0]
	s_nop 0
	v_pk_mul_f32 v[10:11], v[10:11], v[48:49]
	v_pk_fma_f32 v[12:13], v[12:13], v[8:9], 1.0 op_sel_hi:[1,1,0]
	v_mul_f32_e32 v14, v10, v22
	v_fma_f32 v14, v2, v14, 0
	v_mul_f32_e32 v15, v11, v23
	v_pk_mul_f32 v[12:13], v[12:13], v[46:47]
	v_fmac_f32_e32 v14, v3, v15
	v_mul_f32_e32 v15, v12, v24
	v_mul_f32_e32 v16, v13, v25
	v_fmac_f32_e32 v14, v4, v15
	v_fmac_f32_e32 v14, v5, v16
	v_mov_b32_e32 v15, v1
	ds_write_b128 v57, v[10:13] offset:51200
	ds_write_b128 v57, v[18:21] offset:51456
	v_add_f32_dpp v14, v14, v14 row_ror:8 row_mask:0xf bank_mask:0xf bound_ctrl:1
	s_nop 1
	v_add_f32_dpp v14, v14, v14 row_ror:4 row_mask:0xf bank_mask:0xf bound_ctrl:1
	s_nop 1
	v_add_f32_dpp v14, v14, v14 row_ror:2 row_mask:0xf bank_mask:0xf bound_ctrl:1
	s_nop 1
	v_mov_b32_dpp v15, v14 row_ror:1 row_mask:0xf bank_mask:0xf
	s_and_saveexec_b64 s[2:3], s[10:11]
	s_cbranch_execz .LBB0_196
	v_add_u32_e32 v10, 32, v54
	v_sub_u32_e32 v11, 0x1fef, v54
	v_cndmask_b32_e32 v10, v11, v10, vcc
	v_mov_b32_e32 v11, v1
	v_lshl_add_u64 v[10:11], v[34:35], 0, v[10:11]
	v_lshlrev_b64 v[10:11], 5, v[10:11]
	v_add_f32_e32 v12, v14, v15
	v_lshl_add_u64 v[10:11], v[36:37], 0, v[10:11]
	global_store_dword v[10:11], v12, off

; template <int CPL>
; DI void scan_block2(CP p, int layer, int s, int d, int hd, int rowhalf, char* smem) {
;     ...
;     auto load_raw = [&](int c) {
; #pragma unroll
;       for (int u = 0; u < 2; ++u) {
;         const int sj = 8 * sw + 4 * u + (lane >> 4);
;         const int sidc = min(c * 32 + sj, L - 1);
;         const int tok = d == 0 ? sidc : L - 1 - sidc;
;         const u16* base = p.regB + (size_t)(r0 + tok) * 1952 + 4 * q;
;         raw[u][0] = *(const uint2*)(base + aoff0); raw[u][1] = *(const uint2*)(base + aoff1); raw[u][2] = *(const uint2*)(base + aoff2);
;         raw[u][3] = *(const uint2*)(base + aoff3); raw[u][4] = *(const uint2*)(base + aoff4);
;       }
;     };
;     ...
;     for (int c = 0; c < nch; ++c) {
;       if (c + 1 < nch) { stage(c + 1); if (c + 2 < nch) load_raw(c + 2); }
;       if (c >= 1) writeout(c - 1);
;       __syncthreads();
;     }
.LBB0_198:
	s_or_b64 exec, exec, s[2:3]
	v_min_u32_e32 v2, 0x1fcf, v54
	v_add_u32_e32 v3, 64, v2
	v_sub_u32_e32 v2, 0x1fcf, v2
	v_cndmask_b32_e32 v2, v2, v3, vcc
	v_lshl_add_u64 v[44:45], s[66:67], 0, v[0:1]
	v_add_u32_e32 v2, s15, v2
	v_mad_i64_i32 v[2:3], s[2:3], v2, s88, v[44:45]
	v_lshl_add_u64 v[4:5], v[2:3], 0, s[76:77]
	s_mov_b32 s73, s77
	v_lshl_add_u64 v[2:3], v[2:3], 0, s[72:73]
	global_load_dwordx2 v[28:29], v[4:5], off
	global_load_dwordx2 v[50:51], v[4:5], off offset:1024
	global_load_dwordx2 v[48:49], v[4:5], off offset:2048
	global_load_dwordx2 v[6:7], v[2:3], off offset:3072
	v_min_u32_e32 v4, 0x1fcb, v54
	v_add_u32_e32 v5, 0x44, v4
	v_sub_u32_e32 v4, 0x1fcb, v4
	v_cndmask_b32_e32 v4, v4, v5, vcc
	v_add_u32_e32 v4, s15, v4
	v_mad_i64_i32 v[4:5], s[2:3], v4, s88, v[44:45]
	v_lshl_add_u64 v[10:11], v[4:5], 0, s[76:77]
	global_load_dwordx2 v[8:9], v[2:3], off offset:3328
	global_load_dwordx2 v[42:43], v[10:11], off
	global_load_dwordx2 v[46:47], v[10:11], off offset:1024
	global_load_dwordx2 v[40:41], v[10:11], off offset:2048
	v_lshl_add_u64 v[2:3], v[4:5], 0, s[72:73]
	global_load_dwordx2 v[4:5], v[2:3], off offset:3072
	s_nop 0
	global_load_dwordx2 v[2:3], v[2:3], off offset:3328
	s_lshl_b32 s2, s14, 1
	s_add_u32 s2, s78, s2
	s_addc_u32 s3, s79, 0
	s_add_u32 s2, s2, s76
	v_lshrrev_b32_e32 v10, 3, v75
	s_addc_u32 s3, s3, 0
	v_add_u32_e32 v83, v53, v52
	v_cmp_eq_u32_e64 s[44:45], s16, v10
	v_lshlrev_b32_e32 v82, 6, v54
	v_lshl_add_u64 v[38:39], s[2:3], 0, v[0:1]
	v_lshlrev_b32_e32 v75, 6, v77
	v_sub_u32_e32 v84, 0x1feb, v83
	s_mov_b32 s17, 0
	s_mov_b32 s16, 0
	s_mov_b64 s[98:99], exec
	s_mov_b64 exec, -1
	v_and_b32_e32 v105, 63, v179
	v_lshlrev_b32_e32 v105, 2, v105
	v_lshrrev_b32_e32 v106, 6, v179
	v_add_u32_e32 v106, -4, v106
	v_mul_u32_u24_e32 v106, 0x3100, v106
	v_mov_b32_e32 v107, 0xc400
	v_add3_u32 v105, v105, v106, v107
	s_waitcnt lgkmcnt(0)
	ds_read_b32 v109, v105 offset:256
	ds_read_b32 v110, v105 offset:512
	ds_read_b32 v111, v105 offset:768
	ds_read_b32 v112, v105 offset:1024
	s_waitcnt lgkmcnt(0)
	v_mov_b32_e32 v113, v110
	v_rcp_f32_e32 v114, v113
	v_mul_f32_e32 v109, v109, v113
	v_mul_f32_e32 v111, v111, v114
	v_mul_f32_e32 v112, v112, v114
	ds_write_b32 v105, v109 offset:256
	ds_write_b32 v105, v111 offset:768
	ds_write_b32 v105, v112 offset:1024
	ds_read_b32 v108, v105 offset:1568
	ds_read_b32 v109, v105 offset:1824
	ds_read_b32 v110, v105 offset:2080
	ds_read_b32 v111, v105 offset:2336
	ds_read_b32 v112, v105 offset:2592
	s_waitcnt lgkmcnt(0)
	v_mul_f32_e32 v108, v108, v113
	v_mul_f32_e32 v113, v113, v110
	v_rcp_f32_e32 v114, v113
	v_mul_f32_e32 v109, v109, v113
	v_mul_f32_e32 v111, v111, v114
	v_mul_f32_e32 v112, v112, v114
	ds_write_b32 v105, v108 offset:1568
	ds_write_b32 v105, v109 offset:1824
	ds_write_b32 v105, v113 offset:2080
	ds_write_b32 v105, v111 offset:2336
	ds_write_b32 v105, v112 offset:2592
	ds_read_b32 v108, v105 offset:3136
	ds_read_b32 v109, v105 offset:3392
	ds_read_b32 v110, v105 offset:3648
	ds_read_b32 v111, v105 offset:3904
	ds_read_b32 v112, v105 offset:4160
	s_waitcnt lgkmcnt(0)
	v_mul_f32_e32 v108, v108, v113
	v_mul_f32_e32 v113, v113, v110
	v_rcp_f32_e32 v114, v113
	v_mul_f32_e32 v109, v109, v113
	v_mul_f32_e32 v111, v111, v114
	v_mul_f32_e32 v112, v112, v114
	ds_write_b32 v105, v108 offset:3136
	ds_write_b32 v105, v109 offset:3392
	ds_write_b32 v105, v113 offset:3648
	ds_write_b32 v105, v111 offset:3904
	ds_write_b32 v105, v112 offset:4160
	ds_read_b32 v108, v105 offset:4704
	ds_read_b32 v109, v105 offset:4960
	ds_read_b32 v110, v105 offset:5216
	ds_read_b32 v111, v105 offset:5472
	ds_read_b32 v112, v105 offset:5728
	s_waitcnt lgkmcnt(0)
	v_mul_f32_e32 v108, v108, v113
	v_mul_f32_e32 v113, v113, v110
	v_rcp_f32_e32 v114, v113
	v_mul_f32_e32 v109, v109, v113
	v_mul_f32_e32 v111, v111, v114
	v_mul_f32_e32 v112, v112, v114
	ds_write_b32 v105, v108 offset:4704
	ds_write_b32 v105, v109 offset:4960
	ds_write_b32 v105, v113 offset:5216
	ds_write_b32 v105, v111 offset:5472
	ds_write_b32 v105, v112 offset:5728
	ds_read_b32 v108, v105 offset:6272
	ds_read_b32 v109, v105 offset:6528
	ds_read_b32 v110, v105 offset:6784
	ds_read_b32 v111, v105 offset:7040
	ds_read_b32 v112, v105 offset:7296
	s_waitcnt lgkmcnt(0)
	v_mul_f32_e32 v108, v108, v113
	v_mul_f32_e32 v113, v113, v110
	v_rcp_f32_e32 v114, v113
	v_mul_f32_e32 v109, v109, v113
	v_mul_f32_e32 v111, v111, v114
	v_mul_f32_e32 v112, v112, v114
	ds_write_b32 v105, v108 offset:6272
	ds_write_b32 v105, v109 offset:6528
	ds_write_b32 v105, v113 offset:6784
	ds_write_b32 v105, v111 offset:7040
	ds_write_b32 v105, v112 offset:7296
	ds_read_b32 v108, v105 offset:7840
	ds_read_b32 v109, v105 offset:8096
	ds_read_b32 v110, v105 offset:8352
	ds_read_b32 v111, v105 offset:8608
	ds_read_b32 v112, v105 offset:8864
	s_waitcnt lgkmcnt(0)
	v_mul_f32_e32 v108, v108, v113
	v_mul_f32_e32 v113, v113, v110
	v_rcp_f32_e32 v114, v113
	v_mul_f32_e32 v109, v109, v113
	v_mul_f32_e32 v111, v111, v114
	v_mul_f32_e32 v112, v112, v114
	ds_write_b32 v105, v108 offset:7840
	ds_write_b32 v105, v109 offset:8096
	ds_write_b32 v105, v113 offset:8352
	ds_write_b32 v105, v111 offset:8608
	ds_write_b32 v105, v112 offset:8864
	ds_read_b32 v108, v105 offset:9408
	ds_read_b32 v109, v105 offset:9664
	ds_read_b32 v110, v105 offset:9920
	ds_read_b32 v111, v105 offset:10176
	ds_read_b32 v112, v105 offset:10432
	s_waitcnt lgkmcnt(0)
	v_mul_f32_e32 v108, v108, v113
	v_mul_f32_e32 v113, v113, v110
	v_rcp_f32_e32 v114, v113
	v_mul_f32_e32 v109, v109, v113
	v_mul_f32_e32 v111, v111, v114
	v_mul_f32_e32 v112, v112, v114
	ds_write_b32 v105, v108 offset:9408
	ds_write_b32 v105, v109 offset:9664
	ds_write_b32 v105, v113 offset:9920
	ds_write_b32 v105, v111 offset:10176
	ds_write_b32 v105, v112 offset:10432
	ds_read_b32 v108, v105 offset:10976
	ds_read_b32 v110, v105 offset:11488
	ds_read_b32 v111, v105 offset:11744
	ds_read_b32 v112, v105 offset:12000
	s_waitcnt lgkmcnt(0)
	v_mul_f32_e32 v108, v108, v113
	v_mul_f32_e32 v113, v113, v110
	v_rcp_f32_e32 v114, v113
	s_nop 0
	v_mul_f32_e32 v111, v111, v114
	v_mul_f32_e32 v112, v112, v114
	ds_write_b32 v105, v108 offset:10976
	ds_write_b32 v105, v113 offset:11488
	ds_write_b32 v105, v111 offset:11744
	ds_write_b32 v105, v112 offset:12000
	s_mov_b64 exec, s[98:99]
	s_waitcnt lgkmcnt(0)
	s_cselect_b32 s98, 1, 0
	v_mov_b32_e32 v125, s98
	v_add_u32_e32 v120, 1, v120
	v_lshrrev_b32_e32 v121, 6, v179
	v_lshlrev_b32_e32 v121, 2, v121
	v_add_u32_e32 v121, 0x26800, v121
	v_mov_b32_e32 v122, 0x26800
	ds_write_b32 v121, v120
	v_mov_b32_e32 v123, 1000
; template <int CPL>
; DI void scan_block2(CP p, int layer, int s, int d, int hd, int rowhalf, char* smem) {
;     ...
;     for (int c = 0; c < nch; ++c) {
;       if (c + 1 < nch) { stage(c + 1); if (c + 2 < nch) load_raw(c + 2); }
;       if (c >= 1) writeout(c - 1);
;       __syncthreads();
;     }
.Labar_poll_1:
	ds_read_b128 v[116:119], v122
	ds_read_b128 v[126:129], v122 offset:16
	s_waitcnt lgkmcnt(0)
	v_min_u32_e32 v116, v116, v117
	v_min_u32_e32 v118, v118, v119
	v_min_u32_e32 v126, v126, v127
	v_min_u32_e32 v128, v128, v129
	v_min_u32_e32 v116, v116, v118
	v_min_u32_e32 v126, v126, v128
	s_nop 0
	v_min_u32_e32 v116, v116, v126
	s_nop 1
	v_readfirstlane_b32 s98, v116
	v_readfirstlane_b32 s99, v120
	s_nop 0
	s_cmp_ge_u32 s98, s99
	s_cbranch_scc1 .Labar_pass_1
	s_sleep 1
	v_add_u32_e32 v123, -1, v123
	s_nop 1
	v_readfirstlane_b32 s98, v123
	s_nop 0
	s_cmp_gt_i32 s98, 0
	s_cbranch_scc1 .Labar_poll_1
.Labar_pass_1:
	v_readfirstlane_b32 s98, v125
	s_nop 0
	s_cmp_lg_u32 s98, 0
	s_branch .LBB0_200
.LBB0_199:
	s_or_b64 exec, exec, s[2:3]
	s_mov_b64 s[98:99], exec
	s_mov_b64 exec, -1
	v_and_b32_e32 v105, 63, v179
	v_lshlrev_b32_e32 v105, 2, v105
	v_lshrrev_b32_e32 v106, 6, v179
	v_add_u32_e32 v106, -4, v106
	v_mul_u32_u24_e32 v106, 0x3100, v106
	v_mov_b32_e32 v107, 32
	v_and_b32_e32 v107, s16, v107
	v_mul_u32_u24_e32 v107, 0x620, v107
	v_add3_u32 v105, v105, v106, v107
	s_waitcnt lgkmcnt(0)
	ds_read_b32 v109, v105 offset:256
	ds_read_b32 v110, v105 offset:512
	ds_read_b32 v111, v105 offset:768
	ds_read_b32 v112, v105 offset:1024
	s_waitcnt lgkmcnt(0)
	v_mov_b32_e32 v113, v110
	v_rcp_f32_e32 v114, v113
	v_mul_f32_e32 v109, v109, v113
	v_mul_f32_e32 v111, v111, v114
	v_mul_f32_e32 v112, v112, v114
	ds_write_b32 v105, v109 offset:256
	ds_write_b32 v105, v111 offset:768
	ds_write_b32 v105, v112 offset:1024
	ds_read_b32 v108, v105 offset:1568
	ds_read_b32 v109, v105 offset:1824
	ds_read_b32 v110, v105 offset:2080
	ds_read_b32 v111, v105 offset:2336
	ds_read_b32 v112, v105 offset:2592
	s_waitcnt lgkmcnt(0)
	v_mul_f32_e32 v108, v108, v113
	v_mul_f32_e32 v113, v113, v110
	v_rcp_f32_e32 v114, v113
	v_mul_f32_e32 v109, v109, v113
	v_mul_f32_e32 v111, v111, v114
	v_mul_f32_e32 v112, v112, v114
	ds_write_b32 v105, v108 offset:1568
	ds_write_b32 v105, v109 offset:1824
	ds_write_b32 v105, v113 offset:2080
	ds_write_b32 v105, v111 offset:2336
	ds_write_b32 v105, v112 offset:2592
	ds_read_b32 v108, v105 offset:3136
	ds_read_b32 v109, v105 offset:3392
	ds_read_b32 v110, v105 offset:3648
	ds_read_b32 v111, v105 offset:3904
	ds_read_b32 v112, v105 offset:4160
	s_waitcnt lgkmcnt(0)
	v_mul_f32_e32 v108, v108, v113
	v_mul_f32_e32 v113, v113, v110
	v_rcp_f32_e32 v114, v113
	v_mul_f32_e32 v109, v109, v113
	v_mul_f32_e32 v111, v111, v114
	v_mul_f32_e32 v112, v112, v114
	ds_write_b32 v105, v108 offset:3136
	ds_write_b32 v105, v109 offset:3392
	ds_write_b32 v105, v113 offset:3648
	ds_write_b32 v105, v111 offset:3904
	ds_write_b32 v105, v112 offset:4160
	ds_read_b32 v108, v105 offset:4704
	ds_read_b32 v109, v105 offset:4960
	ds_read_b32 v110, v105 offset:5216
	ds_read_b32 v111, v105 offset:5472
	ds_read_b32 v112, v105 offset:5728
	s_waitcnt lgkmcnt(0)
	v_mul_f32_e32 v108, v108, v113
	v_mul_f32_e32 v113, v113, v110
	v_rcp_f32_e32 v114, v113
	v_mul_f32_e32 v109, v109, v113
	v_mul_f32_e32 v111, v111, v114
	v_mul_f32_e32 v112, v112, v114
	ds_write_b32 v105, v108 offset:4704
	ds_write_b32 v105, v109 offset:4960
	ds_write_b32 v105, v113 offset:5216
	ds_write_b32 v105, v111 offset:5472
	ds_write_b32 v105, v112 offset:5728
	ds_read_b32 v108, v105 offset:6272
	ds_read_b32 v109, v105 offset:6528
	ds_read_b32 v110, v105 offset:6784
	ds_read_b32 v111, v105 offset:7040
	ds_read_b32 v112, v105 offset:7296
	s_waitcnt lgkmcnt(0)
	v_mul_f32_e32 v108, v108, v113
	v_mul_f32_e32 v113, v113, v110
	v_rcp_f32_e32 v114, v113
	v_mul_f32_e32 v109, v109, v113
	v_mul_f32_e32 v111, v111, v114
	v_mul_f32_e32 v112, v112, v114
	ds_write_b32 v105, v108 offset:6272
	ds_write_b32 v105, v109 offset:6528
	ds_write_b32 v105, v113 offset:6784
	ds_write_b32 v105, v111 offset:7040
	ds_write_b32 v105, v112 offset:7296
	ds_read_b32 v108, v105 offset:7840
	ds_read_b32 v109, v105 offset:8096
	ds_read_b32 v110, v105 offset:8352
	ds_read_b32 v111, v105 offset:8608
	ds_read_b32 v112, v105 offset:8864
	s_waitcnt lgkmcnt(0)
	v_mul_f32_e32 v108, v108, v113
	v_mul_f32_e32 v113, v113, v110
	v_rcp_f32_e32 v114, v113
	v_mul_f32_e32 v109, v109, v113
	v_mul_f32_e32 v111, v111, v114
	v_mul_f32_e32 v112, v112, v114
	ds_write_b32 v105, v108 offset:7840
	ds_write_b32 v105, v109 offset:8096
	ds_write_b32 v105, v113 offset:8352
	ds_write_b32 v105, v111 offset:8608
	ds_write_b32 v105, v112 offset:8864
	ds_read_b32 v108, v105 offset:9408
	ds_read_b32 v109, v105 offset:9664
	ds_read_b32 v110, v105 offset:9920
	ds_read_b32 v111, v105 offset:10176
	ds_read_b32 v112, v105 offset:10432
	s_waitcnt lgkmcnt(0)
	v_mul_f32_e32 v108, v108, v113
	v_mul_f32_e32 v113, v113, v110
	v_rcp_f32_e32 v114, v113
	v_mul_f32_e32 v109, v109, v113
	v_mul_f32_e32 v111, v111, v114
	v_mul_f32_e32 v112, v112, v114
	ds_write_b32 v105, v108 offset:9408
	ds_write_b32 v105, v109 offset:9664
	ds_write_b32 v105, v113 offset:9920
	ds_write_b32 v105, v111 offset:10176
	ds_write_b32 v105, v112 offset:10432
	ds_read_b32 v108, v105 offset:10976
	ds_read_b32 v110, v105 offset:11488
	ds_read_b32 v111, v105 offset:11744
	ds_read_b32 v112, v105 offset:12000
	s_waitcnt lgkmcnt(0)
	v_mul_f32_e32 v108, v108, v113
	v_mul_f32_e32 v113, v113, v110
	v_rcp_f32_e32 v114, v113
	s_nop 0
	v_mul_f32_e32 v111, v111, v114
	v_mul_f32_e32 v112, v112, v114
	ds_write_b32 v105, v108 offset:10976
	ds_write_b32 v105, v113 offset:11488
	ds_write_b32 v105, v111 offset:11744
	ds_write_b32 v105, v112 offset:12000
	s_mov_b64 exec, s[98:99]
	s_add_i32 s16, s16, 32
	s_addk_i32 s17, 0x800
	s_cmpk_eq_i32 s16, 0x1fc0
	v_subrev_u32_e32 v84, 32, v84
	s_waitcnt lgkmcnt(0)
	s_cselect_b32 s98, 1, 0
	v_mov_b32_e32 v125, s98
	v_add_u32_e32 v120, 1, v120
	v_lshrrev_b32_e32 v121, 6, v179
	v_lshlrev_b32_e32 v121, 2, v121
	v_add_u32_e32 v121, 0x26800, v121
	v_mov_b32_e32 v122, 0x26800
	ds_write_b32 v121, v120
	v_mov_b32_e32 v123, 1000

; template <int CPL>
; DI void scan_block2(CP p, int layer, int s, int d, int hd, int rowhalf, char* smem) {
;     ...
;     for (int c = 0; c < nch; ++c) {
;       if (c + 1 < nch) { stage(c + 1); if (c + 2 < nch) load_raw(c + 2); }
;       if (c >= 1) writeout(c - 1);
;       __syncthreads();
;     }
.Labar_pass_2:
	v_readfirstlane_b32 s98, v125
	s_nop 0
	s_cmp_lg_u32 s98, 0
	s_cbranch_scc1 .LBB0_213

; template <int CPL>
; DI void scan_block2(CP p, int layer, int s, int d, int hd, int rowhalf, char* smem) {
;     ...
;     for (int c = 0; c < nch; ++c) {
;       if (c + 1 < nch) { stage(c + 1); if (c + 2 < nch) load_raw(c + 2); }
;       if (c >= 1) writeout(c - 1);
;       __syncthreads();
;     }
;     writeout(nch - 1);
.LBB0_223:
	s_or_b64 exec, exec, s[2:3]
	v_cmp_gt_i32_e64 s[40:41], 48, v54
	s_and_b64 s[10:11], s[44:45], s[40:41]
	s_mov_b64 s[98:99], exec
	s_mov_b64 exec, -1
	v_and_b32_e32 v105, 63, v179
	v_lshlrev_b32_e32 v105, 2, v105
	v_lshrrev_b32_e32 v106, 6, v179
	v_add_u32_e32 v106, -4, v106
	v_mul_u32_u24_e32 v106, 0x3100, v106
	v_mov_b32_e32 v107, 0x0
	v_add3_u32 v105, v105, v106, v107
	s_waitcnt lgkmcnt(0)
	ds_read_b32 v109, v105 offset:256
	ds_read_b32 v110, v105 offset:512
	ds_read_b32 v111, v105 offset:768
	ds_read_b32 v112, v105 offset:1024
	s_waitcnt lgkmcnt(0)
	v_mov_b32_e32 v113, v110
	v_rcp_f32_e32 v114, v113
	v_mul_f32_e32 v109, v109, v113
	v_mul_f32_e32 v111, v111, v114
	v_mul_f32_e32 v112, v112, v114
	ds_write_b32 v105, v109 offset:256
	ds_write_b32 v105, v111 offset:768
	ds_write_b32 v105, v112 offset:1024
	ds_read_b32 v108, v105 offset:1568
	ds_read_b32 v109, v105 offset:1824
	ds_read_b32 v110, v105 offset:2080
	ds_read_b32 v111, v105 offset:2336
	ds_read_b32 v112, v105 offset:2592
	s_waitcnt lgkmcnt(0)
	v_mul_f32_e32 v108, v108, v113
	v_mul_f32_e32 v113, v113, v110
	v_rcp_f32_e32 v114, v113
	v_mul_f32_e32 v109, v109, v113
	v_mul_f32_e32 v111, v111, v114
	v_mul_f32_e32 v112, v112, v114
	ds_write_b32 v105, v108 offset:1568
	ds_write_b32 v105, v109 offset:1824
	ds_write_b32 v105, v113 offset:2080
	ds_write_b32 v105, v111 offset:2336
	ds_write_b32 v105, v112 offset:2592
	ds_read_b32 v108, v105 offset:3136
	ds_read_b32 v109, v105 offset:3392
	ds_read_b32 v110, v105 offset:3648
	ds_read_b32 v111, v105 offset:3904
	ds_read_b32 v112, v105 offset:4160
	s_waitcnt lgkmcnt(0)
	v_mul_f32_e32 v108, v108, v113
	v_mul_f32_e32 v113, v113, v110
	v_rcp_f32_e32 v114, v113
	v_mul_f32_e32 v109, v109, v113
	v_mul_f32_e32 v111, v111, v114
	v_mul_f32_e32 v112, v112, v114
	ds_write_b32 v105, v108 offset:3136
	ds_write_b32 v105, v109 offset:3392
	ds_write_b32 v105, v113 offset:3648
	ds_write_b32 v105, v111 offset:3904
	ds_write_b32 v105, v112 offset:4160
	ds_read_b32 v108, v105 offset:4704
	ds_read_b32 v109, v105 offset:4960
	ds_read_b32 v110, v105 offset:5216
	ds_read_b32 v111, v105 offset:5472
	ds_read_b32 v112, v105 offset:5728
	s_waitcnt lgkmcnt(0)
	v_mul_f32_e32 v108, v108, v113
	v_mul_f32_e32 v113, v113, v110
	v_rcp_f32_e32 v114, v113
	v_mul_f32_e32 v109, v109, v113
	v_mul_f32_e32 v111, v111, v114
	v_mul_f32_e32 v112, v112, v114
	ds_write_b32 v105, v108 offset:4704
	ds_write_b32 v105, v109 offset:4960
	ds_write_b32 v105, v113 offset:5216
	ds_write_b32 v105, v111 offset:5472
	ds_write_b32 v105, v112 offset:5728
	ds_read_b32 v108, v105 offset:6272
	ds_read_b32 v109, v105 offset:6528
	ds_read_b32 v110, v105 offset:6784
	ds_read_b32 v111, v105 offset:7040
	ds_read_b32 v112, v105 offset:7296
	s_waitcnt lgkmcnt(0)
	v_mul_f32_e32 v108, v108, v113
	v_mul_f32_e32 v113, v113, v110
	v_rcp_f32_e32 v114, v113
	v_mul_f32_e32 v109, v109, v113
	v_mul_f32_e32 v111, v111, v114
	v_mul_f32_e32 v112, v112, v114
	ds_write_b32 v105, v108 offset:6272
	ds_write_b32 v105, v109 offset:6528
	ds_write_b32 v105, v113 offset:6784
	ds_write_b32 v105, v111 offset:7040
	ds_write_b32 v105, v112 offset:7296
	ds_read_b32 v108, v105 offset:7840
	ds_read_b32 v109, v105 offset:8096
	ds_read_b32 v110, v105 offset:8352
	ds_read_b32 v111, v105 offset:8608
	ds_read_b32 v112, v105 offset:8864
	s_waitcnt lgkmcnt(0)
	v_mul_f32_e32 v108, v108, v113
	v_mul_f32_e32 v113, v113, v110
	v_rcp_f32_e32 v114, v113
	v_mul_f32_e32 v109, v109, v113
	v_mul_f32_e32 v111, v111, v114
	v_mul_f32_e32 v112, v112, v114
	ds_write_b32 v105, v108 offset:7840
	ds_write_b32 v105, v109 offset:8096
	ds_write_b32 v105, v113 offset:8352
	ds_write_b32 v105, v111 offset:8608
	ds_write_b32 v105, v112 offset:8864
	ds_read_b32 v108, v105 offset:9408
	ds_read_b32 v109, v105 offset:9664
	ds_read_b32 v110, v105 offset:9920
	ds_read_b32 v111, v105 offset:10176
	ds_read_b32 v112, v105 offset:10432
	s_waitcnt lgkmcnt(0)
	v_mul_f32_e32 v108, v108, v113
	v_mul_f32_e32 v113, v113, v110
	v_rcp_f32_e32 v114, v113
	v_mul_f32_e32 v109, v109, v113
	v_mul_f32_e32 v111, v111, v114
	v_mul_f32_e32 v112, v112, v114
	ds_write_b32 v105, v108 offset:9408
	ds_write_b32 v105, v109 offset:9664
	ds_write_b32 v105, v113 offset:9920
	ds_write_b32 v105, v111 offset:10176
	ds_write_b32 v105, v112 offset:10432
	ds_read_b32 v108, v105 offset:10976
	ds_read_b32 v110, v105 offset:11488
	ds_read_b32 v111, v105 offset:11744
	ds_read_b32 v112, v105 offset:12000
	s_waitcnt lgkmcnt(0)
	v_mul_f32_e32 v108, v108, v113
	v_mul_f32_e32 v113, v113, v110
	v_rcp_f32_e32 v114, v113
	s_nop 0
	v_mul_f32_e32 v111, v111, v114
	v_mul_f32_e32 v112, v112, v114
	ds_write_b32 v105, v108 offset:10976
	ds_write_b32 v105, v113 offset:11488
	ds_write_b32 v105, v111 offset:11744
	ds_write_b32 v105, v112 offset:12000
	s_mov_b64 exec, s[98:99]
	s_waitcnt lgkmcnt(0)
	s_cselect_b32 s98, 1, 0
	v_mov_b32_e32 v125, s98
	v_add_u32_e32 v120, 1, v120
	v_lshrrev_b32_e32 v121, 6, v179
	v_lshlrev_b32_e32 v121, 2, v121
	v_add_u32_e32 v121, 0x26800, v121
	v_mov_b32_e32 v122, 0x26800
	ds_write_b32 v121, v120
	v_mov_b32_e32 v123, 1000

; DI void store4(u16* dst, float a, float b, float c, float d) { *(uint2*)dst = make_uint2(pack2(a, b), pack2(c, d)); }
; template <int CPL>
; DI void scan_block2(CP p, int layer, int s, int d, int hd, int rowhalf, char* smem) {
;     ...
;     auto writeout = [&](int c) {
;       const float* yb = YB + (c & 1) * 2048;
; #pragma unroll
;       for (int u = 0; u < 2; ++u) {
;         const int sj = 8 * sw + 4 * u + (lane >> 4);
;         const int sidx = c * 32 + sj;
;         const bool mine = CPL == 16 ? true : ((q >> 3) == rowhalf);
;         if (sidx < L && mine) {
;           const int tok = d == 0 ? sidx : L - 1 - sidx;
;           const float4 yv = *(const float4*)(yb + sj * 64 + 4 * q);
;           store4((u16*)p.out + (size_t)(r0 + tok) * 1024 + d * 512 + hd * 64 + 4 * q, yv.x, yv.y, yv.z, yv.w);
;         }
;       }
;     };
.Labar_pass_3:
	v_readfirstlane_b32 s98, v125
	s_nop 0
	s_cmp_lg_u32 s98, 0
	s_and_saveexec_b64 s[2:3], s[10:11]
	s_cbranch_execz .LBB0_225
	v_add_u32_e32 v5, 0x1fe0, v54
	v_sub_u32_e32 v6, 47, v54
	v_readlane_b32 s10, v252, 31
	v_cndmask_b32_e32 v5, v6, v5, vcc
	v_add_u32_e32 v10, s15, v5
	v_add3_u32 v6, s10, v4, v2
	ds_read_b128 v[6:9], v6
	v_ashrrev_i32_e32 v11, 31, v10
	v_lshlrev_b64 v[10:11], 11, v[10:11]
	v_lshl_add_u64 v[10:11], v[38:39], 0, v[10:11]
	s_waitcnt lgkmcnt(0)
	v_cvt_pk_bf16_f32 v6, v6, v7
	v_cvt_pk_bf16_f32 v7, v8, v9
	global_store_dwordx2 v[10:11], v[6:7], off

; #define LAS __attribute__((address_space(3)))
; template <bool COOP>
; __global__ void __launch_bounds__(NTHR) mega(Params pp, int lo, int hi) {
;   extern __shared__ __attribute__((aligned(16))) char smem[];
;   const __attribute__((address_space(4))) Params* kp = (const __attribute__((address_space(4))) Params*)__builtin_amdgcn_kernarg_segment_ptr();
;   volatile LAS unsigned* st = (volatile LAS unsigned*)(smem + SMEM_BYTES - 32);
	.amdhsa_kernel _Z4megaILb1EEv6Paramsii
		.amdhsa_group_segment_fixed_size 8448
		.amdhsa_private_segment_fixed_size 0
		.amdhsa_kernarg_size 616
		.amdhsa_user_sgpr_count 2
		.amdhsa_user_sgpr_dispatch_ptr 0
		.amdhsa_user_sgpr_queue_ptr 0
		.amdhsa_user_sgpr_kernarg_segment_ptr 1
		.amdhsa_user_sgpr_dispatch_id 0
		.amdhsa_user_sgpr_kernarg_preload_length 0
		.amdhsa_user_sgpr_kernarg_preload_offset 0
		.amdhsa_user_sgpr_private_segment_size 0
		.amdhsa_uses_dynamic_stack 0
		.amdhsa_enable_private_segment 0
		.amdhsa_system_sgpr_workgroup_id_x 1
		.amdhsa_system_sgpr_workgroup_id_y 0
		.amdhsa_system_sgpr_workgroup_id_z 0
		.amdhsa_system_sgpr_workgroup_info 0
		.amdhsa_system_vgpr_workitem_id 2
		.amdhsa_next_free_vgpr 256
		.amdhsa_next_free_sgpr 100
		.amdhsa_accum_offset 256
		.amdhsa_reserve_vcc 1
		.amdhsa_float_round_mode_32 0
		.amdhsa_float_round_mode_16_64 0
		.amdhsa_float_denorm_mode_32 3
		.amdhsa_float_denorm_mode_16_64 3
		.amdhsa_dx10_clamp 1
		.amdhsa_ieee_mode 1
		.amdhsa_fp16_overflow 0
		.amdhsa_tg_split 0
		.amdhsa_exception_fp_ieee_invalid_op 0
		.amdhsa_exception_fp_denorm_src 0
		.amdhsa_exception_fp_ieee_div_zero 0
		.amdhsa_exception_fp_ieee_overflow 0
		.amdhsa_exception_fp_ieee_underflow 0
		.amdhsa_exception_fp_ieee_inexact 0
		.amdhsa_exception_int_div_zero 0
	.end_amdhsa_kernel

; #define LAS __attribute__((address_space(3)))
; template <bool COOP>
; __global__ void __launch_bounds__(NTHR) mega(Params pp, int lo, int hi) {
;   extern __shared__ __attribute__((aligned(16))) char smem[];
;   const __attribute__((address_space(4))) Params* kp = (const __attribute__((address_space(4))) Params*)__builtin_amdgcn_kernarg_segment_ptr();
;   volatile LAS unsigned* st = (volatile LAS unsigned*)(smem + SMEM_BYTES - 32);
amdhsa.kernels:
  - .agpr_count:     0
    .args:
      - .offset:         0
        .size:           352
        .value_kind:     by_value
      - .offset:         352
        .size:           4
        .value_kind:     by_value
      - .offset:         356
        .size:           4
        .value_kind:     by_value
      - .offset:         360
        .size:           4
        .value_kind:     hidden_block_count_x
      - .offset:         364
        .size:           4
        .value_kind:     hidden_block_count_y
      - .offset:         368
        .size:           4
        .value_kind:     hidden_block_count_z
      - .offset:         372
        .size:           2
        .value_kind:     hidden_group_size_x
      - .offset:         374
        .size:           2
        .value_kind:     hidden_group_size_y
      - .offset:         376
        .size:           2
        .value_kind:     hidden_group_size_z
      - .offset:         378
        .size:           2
        .value_kind:     hidden_remainder_x
      - .offset:         380
        .size:           2
        .value_kind:     hidden_remainder_y
      - .offset:         382
        .size:           2
        .value_kind:     hidden_remainder_z
      - .offset:         400
        .size:           8
        .value_kind:     hidden_global_offset_x
      - .offset:         408
        .size:           8
        .value_kind:     hidden_global_offset_y
      - .offset:         416
        .size:           8
        .value_kind:     hidden_global_offset_z
      - .offset:         424
        .size:           2
        .value_kind:     hidden_grid_dims
      - .offset:         448
        .size:           8
        .value_kind:     hidden_multigrid_sync_arg
      - .offset:         480
        .size:           4
        .value_kind:     hidden_dynamic_lds_size
    .group_segment_fixed_size: 8448
    .kernarg_segment_align: 8
    .kernarg_segment_size: 616
    .language:       OpenCL C
    .language_version:
      - 2
      - 0
    .max_flat_workgroup_size: 512
    .name:           _Z4megaILb1EEv6Paramsii
    .private_segment_fixed_size: 0
    .sgpr_count:     106
    .sgpr_spill_count: 137
    .symbol:         _Z4megaILb1EEv6Paramsii.kd
    .uniform_work_group_size: 1
    .uses_dynamic_stack: false
    .vgpr_count:     256
    .vgpr_spill_count: 0
    .wavefront_size: 64
